# v13 + nt (streaming) hints on read-once norm/P4-X loads and final-output stores
# speedup vs baseline: 1.0120x; 1.0037x over previous
; template <bool BF> DI void norm_rows4(float* src, const float* gw, bf16* dstb, int r0, int stride, int lane) {
;     f32x4 v[4][4];
; #pragma unroll
;     for (int k = 0; k < 4; ++k) { const int r = r0 + k * stride;
; #pragma unroll
;         for (int j = 0; j < 4; ++j) v[k][j] = r < M ? *(const f32x4*)(src + (size_t)r * D + 4 * lane + 256 * j) : (f32x4){0.f, 0.f, 0.f, 0.f}; }
;     f32x4 gg[4];
; #pragma unroll
;     for (int j = 0; j < 4; ++j) gg[j] = *(const f32x4*)(gw + 4 * lane + 256 * j);
; #pragma unroll
;     for (int k = 0; k < 4; ++k) { const int r = r0 + k * stride; float s = 0.f;
; #pragma unroll
;         for (int j = 0; j < 4; ++j) s += (v[k][j].x * v[k][j].x + v[k][j].y * v[k][j].y) + (v[k][j].z * v[k][j].z + v[k][j].w * v[k][j].w);
;         const float rs = 1.f / sqrtf(wave_sum(s) * (1.f / D) + 1e-6f);
.LBB0_108:
	s_ashr_i32 s17, s16, 31
	s_lshl_b64 s[0:1], s[16:17], 12
	v_lshl_add_u64 v[2:3], v[82:83], 0, s[0:1]
	global_load_dwordx4 v[78:81], v[2:3], off nt
	global_load_dwordx4 v[74:77], v[2:3], off offset:1024 nt
	global_load_dwordx4 v[66:69], v[2:3], off offset:2048 nt
	global_load_dwordx4 v[58:61], v[2:3], off offset:3072 nt
	s_add_i32 s18, s16, s74
	s_cmp_lt_i32 s18, 0x10000
	s_cselect_b64 s[0:1], -1, 0
	s_ashr_i32 s19, s18, 31
	s_lshl_b64 s[2:3], s[18:19], 12
	s_cmp_gt_i32 s18, 0xffff
	v_lshl_add_u64 v[2:3], v[82:83], 0, s[2:3]
	v_mov_b32_e32 v38, 0
	v_mov_b32_e32 v39, 0
	v_mov_b32_e32 v40, 0
	v_mov_b32_e32 v41, 0
	s_cbranch_scc1 .LBB0_110
	global_load_dwordx4 v[38:41], v[2:3], off nt
.LBB0_110:
	v_cndmask_b32_e64 v4, 0, 1, s[0:1]
	v_mov_b32_e32 v34, 0
	v_cmp_ne_u32_e64 s[6:7], 1, v4
	s_andn2_b64 vcc, exec, s[0:1]
	v_mov_b32_e32 v42, 0
	v_mov_b32_e32 v43, 0
	v_mov_b32_e32 v44, 0
	v_mov_b32_e32 v45, 0
	s_cbranch_vccnz .LBB0_112
	global_load_dwordx4 v[42:45], v[2:3], off offset:1024 nt
.LBB0_112:
	s_and_b64 vcc, exec, s[6:7]
	v_mov_b32_e32 v35, 0
	v_mov_b32_e32 v36, 0
	v_mov_b32_e32 v37, 0
	s_cbranch_vccnz .LBB0_114
	global_load_dwordx4 v[34:37], v[2:3], off offset:2048 nt
.LBB0_114:
	v_mov_b32_e32 v10, 0
	s_and_b64 vcc, exec, s[6:7]
	v_mov_b32_e32 v50, 0
	v_mov_b32_e32 v51, 0
	v_mov_b32_e32 v52, 0
	v_mov_b32_e32 v53, 0
	s_cbranch_vccnz .LBB0_116
	global_load_dwordx4 v[50:53], v[2:3], off offset:3072 nt
.LBB0_116:
	s_add_i32 s22, s13, s16
	s_cmp_lt_i32 s22, 0x10000
	s_cselect_b64 s[0:1], -1, 0
	s_ashr_i32 s23, s22, 31
	s_lshl_b64 s[2:3], s[22:23], 12
	s_cmp_gt_i32 s22, 0xffff
	v_lshl_add_u64 v[4:5], v[82:83], 0, s[2:3]
	s_waitcnt lgkmcnt(0)
	v_mov_b32_e32 v11, 0
	v_mov_b32_e32 v12, 0
	v_mov_b32_e32 v13, 0
	s_cbranch_scc1 .LBB0_118
	global_load_dwordx4 v[10:13], v[4:5], off nt
.LBB0_118:
	v_cndmask_b32_e64 v2, 0, 1, s[0:1]
	v_mov_b32_e32 v22, 0
	v_cmp_ne_u32_e64 s[4:5], 1, v2
	s_andn2_b64 vcc, exec, s[0:1]
	v_mov_b32_e32 v26, 0
	v_mov_b32_e32 v27, 0
	v_mov_b32_e32 v28, 0
	v_mov_b32_e32 v29, 0
	s_cbranch_vccnz .LBB0_120
	global_load_dwordx4 v[26:29], v[4:5], off offset:1024 nt
.LBB0_120:
	s_and_b64 vcc, exec, s[4:5]
	v_mov_b32_e32 v23, 0
	v_mov_b32_e32 v24, 0
	v_mov_b32_e32 v25, 0
	s_cbranch_vccnz .LBB0_122
	global_load_dwordx4 v[22:25], v[4:5], off offset:2048 nt
.LBB0_122:
	v_mov_b32_e32 v2, 0
	s_and_b64 vcc, exec, s[4:5]
	v_mov_b32_e32 v30, 0
	v_mov_b32_e32 v31, 0
	v_mov_b32_e32 v32, 0
	v_mov_b32_e32 v33, 0
	s_cbranch_vccnz .LBB0_124
	global_load_dwordx4 v[30:33], v[4:5], off offset:3072 nt
.LBB0_124:
	s_mul_i32 s0, s8, 24
	s_add_i32 s20, s0, s16
	s_cmp_lt_i32 s20, 0x10000
	s_cselect_b64 s[0:1], -1, 0
	s_ashr_i32 s21, s20, 31
	s_lshl_b64 s[2:3], s[20:21], 12
	s_cmp_gt_i32 s20, 0xffff
	v_lshl_add_u64 v[46:47], v[82:83], 0, s[2:3]
	v_mov_b32_e32 v3, 0
	v_mov_b32_e32 v4, 0
	v_mov_b32_e32 v5, 0
	s_cbranch_scc1 .LBB0_126
	global_load_dwordx4 v[2:5], v[46:47], off nt
.LBB0_126:
	v_cndmask_b32_e64 v7, 0, 1, s[0:1]
	v_mov_b32_e32 v6, 0
	v_cmp_ne_u32_e64 s[2:3], 1, v7
	s_andn2_b64 vcc, exec, s[0:1]
	v_mov_b32_e32 v14, 0
	v_mov_b32_e32 v15, 0
	v_mov_b32_e32 v16, 0
	v_mov_b32_e32 v17, 0
	s_cbranch_vccnz .LBB0_128
	global_load_dwordx4 v[14:17], v[46:47], off offset:1024 nt
.LBB0_128:
	s_and_b64 vcc, exec, s[2:3]
	v_mov_b32_e32 v7, 0
	v_mov_b32_e32 v8, 0
	s_waitcnt lgkmcnt(0)
	v_mov_b32_e32 v9, 0
	s_cbranch_vccnz .LBB0_130
	global_load_dwordx4 v[6:9], v[46:47], off offset:2048 nt
.LBB0_130:
	v_mov_b32_e32 v18, 0
	s_and_b64 vcc, exec, s[2:3]
	v_mov_b32_e32 v19, 0
	v_mov_b32_e32 v20, 0
	v_mov_b32_e32 v21, 0
	s_cbranch_vccnz .LBB0_132
	global_load_dwordx4 v[18:21], v[46:47], off offset:3072 nt
.LBB0_132:
	s_waitcnt vmcnt(3)
	v_pk_mul_f32 v[54:55], v[80:81], v[80:81]
	v_pk_mul_f32 v[56:57], v[78:79], v[78:79]
	global_load_dwordx4 v[46:49], v[84:85], off nt
	global_load_dwordx4 v[70:73], v[84:85], off offset:1024 nt
	v_pk_mov_b32 v[62:63], v[56:57], v[54:55] op_sel:[1,0]
	v_mov_b32_e32 v57, v55
	v_pk_add_f32 v[54:55], v[62:63], v[56:57]
	s_waitcnt vmcnt(4)
	v_pk_mul_f32 v[56:57], v[76:77], v[76:77]
	v_pk_mul_f32 v[62:63], v[74:75], v[74:75]
	v_pk_add_f32 v[54:55], v[54:55], v[54:55] op_sel:[0,1] op_sel_hi:[1,0]
	v_pk_mov_b32 v[64:65], v[62:63], v[56:57] op_sel:[1,0]
	v_mov_b32_e32 v63, v57
	v_pk_add_f32 v[56:57], v[64:65], v[62:63]
	s_waitcnt vmcnt(2)
	v_mul_f32_e32 v62, v58, v58
	v_mul_f32_e32 v63, v59, v59
	v_pk_add_f32 v[56:57], v[56:57], v[56:57] op_sel:[0,1] op_sel_hi:[1,0]
	v_mov_b32_e32 v55, v62
	v_mov_b32_e32 v57, v63
	v_pk_add_f32 v[54:55], v[54:55], v[56:57]
	v_mul_f32_e32 v56, v67, v67
	v_mul_f32_e32 v62, v69, v69
	v_mul_f32_e32 v64, v60, v60
	v_mul_f32_e32 v65, v61, v61
	v_pk_fma_f32 v[56:57], v[66:67], v[66:67], v[56:57] op_sel_hi:[1,1,0]
	v_pk_fma_f32 v[62:63], v[68:69], v[68:69], v[62:63] op_sel_hi:[1,1,0]
	v_mov_b32_e32 v57, v64
	v_mov_b32_e32 v63, v65
	v_pk_add_f32 v[56:57], v[56:57], v[62:63]
	global_load_dwordx4 v[62:65], v[84:85], off offset:2048 nt
	v_pk_add_f32 v[54:55], v[54:55], v[56:57]
	s_lshl_b64 s[16:17], s[16:17], 11
	v_add_f32_e32 v54, v54, v55
	ds_bpermute_b32 v55, v1, v54
	s_waitcnt lgkmcnt(0)
	v_add_f32_e32 v54, v54, v55
	ds_bpermute_b32 v55, v89, v54
	s_waitcnt lgkmcnt(0)
	v_add_f32_e32 v54, v54, v55
	ds_bpermute_b32 v55, v90, v54
	s_waitcnt lgkmcnt(0)
	v_add_f32_e32 v54, v54, v55
	ds_bpermute_b32 v55, v91, v54
	s_waitcnt lgkmcnt(0)
	v_add_f32_e32 v54, v54, v55
	ds_bpermute_b32 v55, v92, v54
	s_waitcnt lgkmcnt(0)
	v_add_f32_e32 v54, v54, v55
	ds_bpermute_b32 v55, v93, v54
	s_waitcnt lgkmcnt(0)
; DI unsigned cvtpk(float lo, float hi) { f32x2_t v = {lo, hi}; bf16x2_t b = __builtin_convertvector(v, bf16x2_t); return __builtin_bit_cast(unsigned, b); }
; template <bool BF> DI void norm_rows4(float* src, const float* gw, bf16* dstb, int r0, int stride, int lane) {
;     ...
;     for (int k = 0; k < 4; ++k) { const int r = r0 + k * stride; float s = 0.f;
; #pragma unroll
;         for (int j = 0; j < 4; ++j) s += (v[k][j].x * v[k][j].x + v[k][j].y * v[k][j].y) + (v[k][j].z * v[k][j].z + v[k][j].w * v[k][j].w);
;         const float rs = 1.f / sqrtf(wave_sum(s) * (1.f / D) + 1e-6f);
;         if (r < M) {
; #pragma unroll
;             for (int j = 0; j < 4; ++j) {
;                 const f32x4 y = (f32x4){v[k][j].x * rs * gg[j].x, v[k][j].y * rs * gg[j].y, v[k][j].z * rs * gg[j].z, v[k][j].w * rs * gg[j].w};
;                 if (BF) { u32x2 w; w.x = cvtpk(y.x, y.y); w.y = cvtpk(y.z, y.w); *(u32x2*)(dstb + (size_t)r * D + 4 * lane + 256 * j) = w; }
;                 else *(f32x4*)(src + (size_t)r * D + 4 * lane + 256 * j) = y;
;             }
;         }
;     }
	v_add_f32_e32 v54, v54, v55
	v_fmamk_f32 v54, v54, 0x3a800000, v94
	v_mul_f32_e32 v55, 0x4f800000, v54
	v_cmp_gt_f32_e32 vcc, s24, v54
	s_nop 1
	v_cndmask_b32_e32 v96, v54, v55, vcc
	global_load_dwordx4 v[54:57], v[84:85], off offset:3072 nt
	v_sqrt_f32_e32 v97, v96
	s_nop 0
	v_add_u32_e32 v98, -1, v97
	v_add_u32_e32 v99, 1, v97
	v_fma_f32 v100, -v98, v97, v96
	v_fma_f32 v101, -v99, v97, v96
	v_cmp_ge_f32_e64 s[0:1], 0, v100
	s_nop 1
	v_cndmask_b32_e64 v97, v97, v98, s[0:1]
	v_cmp_lt_f32_e64 s[0:1], 0, v101
	s_nop 1
	v_cndmask_b32_e64 v97, v97, v99, s[0:1]
	v_mul_f32_e32 v98, 0x37800000, v97
	v_cndmask_b32_e32 v97, v97, v98, vcc
	v_cmp_class_f32_e32 vcc, v96, v95
	s_nop 1
	v_cndmask_b32_e32 v98, v97, v96, vcc
	v_div_scale_f32 v99, s[0:1], v98, v98, 1.0
	v_rcp_f32_e32 v100, v99
	v_div_scale_f32 v101, vcc, 1.0, v98, 1.0
	v_lshl_add_u64 v[96:97], v[86:87], 0, s[16:17]
	v_fma_f32 v102, -v99, v100, 1.0
	v_fmac_f32_e32 v100, v102, v100
	v_mul_f32_e32 v102, v101, v100
	v_fma_f32 v103, -v99, v102, v101
	v_fmac_f32_e32 v102, v103, v100
	v_fma_f32 v99, -v99, v102, v101
	v_div_fmas_f32 v99, v99, v100, v102
	v_div_fixup_f32 v98, v99, v98, 1.0
	v_pk_mul_f32 v[78:79], v[78:79], v[98:99] op_sel_hi:[1,0]
	v_pk_mul_f32 v[80:81], v[80:81], v[98:99] op_sel_hi:[1,0]
	s_waitcnt vmcnt(3)
	v_pk_mul_f32 v[78:79], v[46:47], v[78:79]
	v_mul_f32_e32 v99, v41, v41
	v_cvt_pk_bf16_f32 v78, v78, v79
	v_mul_f32_e32 v79, v39, v39
	v_fmac_f32_e32 v79, v38, v38
	v_fmac_f32_e32 v99, v40, v40
	v_add_f32_e32 v79, v79, v99
	v_mul_f32_e32 v99, v43, v43
	v_mul_f32_e32 v100, v45, v45
	v_fmac_f32_e32 v99, v42, v42
	v_fmac_f32_e32 v100, v44, v44
	v_add_f32_e32 v99, v99, v100
	v_add_f32_e32 v79, v79, v99
	v_mul_f32_e32 v99, v35, v35
	v_mul_f32_e32 v100, v37, v37
	v_fmac_f32_e32 v99, v34, v34
	v_fmac_f32_e32 v100, v36, v36
	v_add_f32_e32 v99, v99, v100
	v_add_f32_e32 v79, v79, v99
	v_mul_f32_e32 v99, v51, v51
	v_mul_f32_e32 v100, v53, v53
	v_fmac_f32_e32 v99, v50, v50
	v_fmac_f32_e32 v100, v52, v52
	v_add_f32_e32 v99, v99, v100
	v_add_f32_e32 v99, v79, v99
	ds_bpermute_b32 v100, v1, v99
	v_pk_mul_f32 v[80:81], v[48:49], v[80:81]
	v_pk_mul_f32 v[74:75], v[74:75], v[98:99] op_sel_hi:[1,0]
	v_cvt_pk_bf16_f32 v79, v80, v81
	global_store_dwordx2 v[96:97], v[78:79], off
	s_waitcnt lgkmcnt(0)
	v_add_f32_e32 v78, v99, v100
	ds_bpermute_b32 v79, v89, v78
	v_pk_mul_f32 v[76:77], v[76:77], v[98:99] op_sel_hi:[1,0]
	s_waitcnt vmcnt(3)
	v_pk_mul_f32 v[74:75], v[70:71], v[74:75]
	v_pk_mul_f32 v[76:77], v[72:73], v[76:77]
	v_cvt_pk_bf16_f32 v74, v74, v75
	v_cvt_pk_bf16_f32 v75, v76, v77
	s_waitcnt lgkmcnt(0)
	v_add_f32_e32 v76, v78, v79
	ds_bpermute_b32 v77, v90, v76
	global_store_dwordx2 v[96:97], v[74:75], off offset:512
	v_pk_mul_f32 v[66:67], v[66:67], v[98:99] op_sel_hi:[1,0]
	v_pk_mul_f32 v[68:69], v[68:69], v[98:99] op_sel_hi:[1,0]
	s_waitcnt vmcnt(3)
	v_pk_mul_f32 v[66:67], v[62:63], v[66:67]
	s_waitcnt lgkmcnt(0)
	v_add_f32_e32 v74, v76, v77
	ds_bpermute_b32 v75, v91, v74
	v_pk_mul_f32 v[68:69], v[64:65], v[68:69]
	v_cvt_pk_bf16_f32 v66, v66, v67
	v_cvt_pk_bf16_f32 v67, v68, v69
	v_pk_mul_f32 v[58:59], v[58:59], v[98:99] op_sel_hi:[1,0]
	s_waitcnt lgkmcnt(0)
	v_add_f32_e32 v68, v74, v75
	ds_bpermute_b32 v69, v92, v68
	global_store_dwordx2 v[96:97], v[66:67], off offset:1024
	s_waitcnt vmcnt(3)
	v_pk_mul_f32 v[66:67], v[54:55], v[58:59]
	v_pk_mul_f32 v[58:59], v[60:61], v[98:99] op_sel_hi:[1,0]
	v_cvt_pk_bf16_f32 v66, v66, v67
	v_pk_mul_f32 v[60:61], v[56:57], v[58:59]
	s_waitcnt lgkmcnt(0)
	v_add_f32_e32 v58, v68, v69
	ds_bpermute_b32 v59, v93, v58
	v_cvt_pk_bf16_f32 v67, v60, v61
	s_and_b64 vcc, exec, s[6:7]
	global_store_dwordx2 v[96:97], v[66:67], off offset:1536
	s_cbranch_vccnz .LBB0_134
	s_waitcnt lgkmcnt(0)
	v_add_f32_e32 v58, v58, v59
	v_fmamk_f32 v58, v58, 0x3a800000, v94
	v_mul_f32_e32 v59, 0x4f800000, v58
	v_cmp_gt_f32_e32 vcc, s24, v58
	s_nop 1
	v_cndmask_b32_e32 v58, v58, v59, vcc
	v_sqrt_f32_e32 v59, v58
	s_nop 0
	v_add_u32_e32 v60, -1, v59
	v_fma_f32 v66, -v60, v59, v58
	v_add_u32_e32 v61, 1, v59
	v_cmp_ge_f32_e64 s[0:1], 0, v66
	s_nop 1
	v_cndmask_b32_e64 v60, v59, v60, s[0:1]
	v_fma_f32 v59, -v61, v59, v58
	v_cmp_lt_f32_e64 s[0:1], 0, v59
	s_nop 1
	v_cndmask_b32_e64 v59, v60, v61, s[0:1]
	v_mul_f32_e32 v60, 0x37800000, v59
	v_cndmask_b32_e32 v59, v59, v60, vcc
	v_cmp_class_f32_e32 vcc, v58, v95
	s_nop 1
	v_cndmask_b32_e32 v58, v59, v58, vcc
	v_div_scale_f32 v59, s[0:1], v58, v58, 1.0
	v_rcp_f32_e32 v60, v59
	s_lshl_b64 s[0:1], s[18:19], 11
	v_fma_f32 v61, -v59, v60, 1.0
	v_fmac_f32_e32 v60, v61, v60
	v_div_scale_f32 v61, vcc, 1.0, v58, 1.0
	v_mul_f32_e32 v66, v61, v60
	v_fma_f32 v67, -v59, v66, v61
	v_fmac_f32_e32 v66, v67, v60
	v_fma_f32 v59, -v59, v66, v61
	v_div_fmas_f32 v59, v59, v60, v66
	v_div_fixup_f32 v58, v59, v58, 1.0
	v_pk_mul_f32 v[38:39], v[38:39], v[58:59] op_sel_hi:[1,0]
	v_pk_mul_f32 v[40:41], v[40:41], v[58:59] op_sel_hi:[1,0]
	v_pk_mul_f32 v[34:35], v[34:35], v[58:59] op_sel_hi:[1,0]
	v_pk_mul_f32 v[36:37], v[36:37], v[58:59] op_sel_hi:[1,0]
	v_pk_mul_f32 v[38:39], v[46:47], v[38:39]
	v_pk_mul_f32 v[40:41], v[48:49], v[40:41]
	v_pk_mul_f32 v[34:35], v[62:63], v[34:35]
	v_pk_mul_f32 v[36:37], v[64:65], v[36:37]
	v_lshl_add_u64 v[60:61], v[86:87], 0, s[0:1]
	v_cvt_pk_bf16_f32 v38, v38, v39
	v_cvt_pk_bf16_f32 v39, v40, v41
	v_cvt_pk_bf16_f32 v34, v34, v35
	v_cvt_pk_bf16_f32 v35, v36, v37
	global_store_dwordx2 v[60:61], v[38:39], off
	v_pk_mul_f32 v[38:39], v[42:43], v[58:59] op_sel_hi:[1,0]
	v_pk_mul_f32 v[40:41], v[44:45], v[58:59] op_sel_hi:[1,0]
	global_store_dwordx2 v[60:61], v[34:35], off offset:1024
	v_pk_mul_f32 v[34:35], v[50:51], v[58:59] op_sel_hi:[1,0]
	v_pk_mul_f32 v[36:37], v[52:53], v[58:59] op_sel_hi:[1,0]
	v_pk_mul_f32 v[38:39], v[70:71], v[38:39]
	v_pk_mul_f32 v[40:41], v[72:73], v[40:41]
	v_pk_mul_f32 v[34:35], v[54:55], v[34:35]
	v_pk_mul_f32 v[36:37], v[56:57], v[36:37]
	v_cvt_pk_bf16_f32 v38, v38, v39
	v_cvt_pk_bf16_f32 v39, v40, v41
	v_cvt_pk_bf16_f32 v34, v34, v35
	v_cvt_pk_bf16_f32 v35, v36, v37
	global_store_dwordx2 v[60:61], v[38:39], off offset:512
	global_store_dwordx2 v[60:61], v[34:35], off offset:1536

;     __device__ __forceinline__ void operator()(const f32x4 (&acc)[2][2][4][2], const pg8::Unit& u, int wr, int wc, int fr, int fq) const {
;         const int row0 = u.pm * 256 + wr * 64 + fr, col0 = u.pn * 256 + wc * 32 + 8 * fq;
; #pragma unroll
;         for (int ai = 0; ai < 2; ++ai)
; #pragma unroll
;             for (int m = 0; m < 4; ++m)
; #pragma unroll
;                 for (int bj = 0; bj < 2; ++bj) { const size_t idx = (size_t)(row0 + ai * 128 + m * 16) * D + col0 + bj * 128;
;                     const f32x4 a = *(const f32x4*)(X + idx), c = *(const f32x4*)(X + idx + 4);
;                     *(f32x4*)(O + idx) = a + acc[ai][bj][m][0]; *(f32x4*)(O + idx + 4) = c + acc[ai][bj][m][1]; }
.LBB0_619:
	v_lshl_add_u32 v144, s37, 8, v146
	v_lshl_or_b32 v142, s36, 8, v149
	v_ashrrev_i32_e32 v145, 31, v144
	v_ashrrev_i32_e32 v143, 31, v142
	v_lshlrev_b64 v[140:141], 10, v[144:145]
	v_lshl_add_u64 v[140:141], v[140:141], 0, v[142:143]
	v_lshlrev_b64 v[140:141], 2, v[140:141]
	v_readlane_b32 s36, v245, 0
	v_readlane_b32 s37, v245, 1
	s_andn2_b64 vcc, exec, s[2:3]
	v_readlane_b32 s38, v245, 2
	v_readlane_b32 s39, v245, 3
	v_mov_b32_e32 v168, v140
	v_add_u32_e32 v169, 0x10000, v140
	v_add_u32_e32 v170, 0x20000, v140
	v_add_u32_e32 v171, 0x30000, v140
	v_add_u32_e32 v246, 0x80000, v140
	v_add_u32_e32 v247, 0x90000, v140
	v_add_u32_e32 v248, 0xa0000, v140
	v_add_u32_e32 v249, 0xb0000, v140
	global_load_dwordx4 v[186:189], v168, s[4:5] nt
	global_load_dwordx4 v[190:193], v168, s[4:5] offset:16 nt
	global_load_dwordx4 v[194:197], v168, s[4:5] offset:512 nt
	global_load_dwordx4 v[198:201], v168, s[4:5] offset:528 nt
	global_load_dwordx4 v[202:205], v169, s[4:5] nt
	global_load_dwordx4 v[206:209], v169, s[4:5] offset:16 nt
	global_load_dwordx4 v[210:213], v169, s[4:5] offset:512 nt
	global_load_dwordx4 v[214:217], v169, s[4:5] offset:528 nt
	global_load_dwordx4 v[218:221], v170, s[4:5] nt
	global_load_dwordx4 v[222:225], v170, s[4:5] offset:16 nt
	global_load_dwordx4 v[226:229], v170, s[4:5] offset:512 nt
	global_load_dwordx4 v[230:233], v170, s[4:5] offset:528 nt
	global_load_dwordx4 v[234:237], v171, s[4:5] nt
	global_load_dwordx4 v[238:241], v171, s[4:5] offset:16 nt
	global_load_dwordx4 v[160:163], v171, s[4:5] offset:512 nt
	global_load_dwordx4 v[164:167], v171, s[4:5] offset:528 nt
	s_waitcnt vmcnt(14)
	v_pk_add_f32 v[126:127], v[126:127], v[186:187]
	v_pk_add_f32 v[128:129], v[128:129], v[188:189]
	v_pk_add_f32 v[122:123], v[122:123], v[190:191]
	v_pk_add_f32 v[124:125], v[124:125], v[192:193]
	global_store_dwordx4 v168, v[126:129], s[36:37]
	global_store_dwordx4 v168, v[122:125], s[36:37] offset:16
	global_load_dwordx4 v[186:189], v246, s[4:5] nt
	global_load_dwordx4 v[190:193], v246, s[4:5] offset:16 nt
	s_waitcnt vmcnt(16)
	v_pk_add_f32 v[118:119], v[118:119], v[194:195]
	v_pk_add_f32 v[120:121], v[120:121], v[196:197]
	v_pk_add_f32 v[114:115], v[114:115], v[198:199]
	v_pk_add_f32 v[116:117], v[116:117], v[200:201]
	global_store_dwordx4 v168, v[118:121], s[36:37] offset:512
	global_store_dwordx4 v168, v[114:117], s[36:37] offset:528
	global_load_dwordx4 v[194:197], v246, s[4:5] offset:512 nt
	global_load_dwordx4 v[198:201], v246, s[4:5] offset:528 nt
	s_waitcnt vmcnt(18)
	v_pk_add_f32 v[110:111], v[110:111], v[202:203]
	v_pk_add_f32 v[112:113], v[112:113], v[204:205]
	v_pk_add_f32 v[106:107], v[106:107], v[206:207]
	v_pk_add_f32 v[108:109], v[108:109], v[208:209]
	global_store_dwordx4 v169, v[110:113], s[36:37]
	global_store_dwordx4 v169, v[106:109], s[36:37] offset:16
	global_load_dwordx4 v[202:205], v247, s[4:5] nt
	global_load_dwordx4 v[206:209], v247, s[4:5] offset:16 nt
	s_waitcnt vmcnt(20)
	v_pk_add_f32 v[102:103], v[102:103], v[210:211]
	v_pk_add_f32 v[104:105], v[104:105], v[212:213]
	v_pk_add_f32 v[98:99], v[98:99], v[214:215]
	v_pk_add_f32 v[100:101], v[100:101], v[216:217]
	global_store_dwordx4 v169, v[102:105], s[36:37] offset:512
	global_store_dwordx4 v169, v[98:101], s[36:37] offset:528
	global_load_dwordx4 v[210:213], v247, s[4:5] offset:512 nt
	global_load_dwordx4 v[214:217], v247, s[4:5] offset:528 nt
	s_waitcnt vmcnt(22)
	v_pk_add_f32 v[94:95], v[94:95], v[218:219]
	v_pk_add_f32 v[96:97], v[96:97], v[220:221]
	v_pk_add_f32 v[90:91], v[90:91], v[222:223]
	v_pk_add_f32 v[92:93], v[92:93], v[224:225]
	global_store_dwordx4 v170, v[94:97], s[36:37]
	global_store_dwordx4 v170, v[90:93], s[36:37] offset:16
	global_load_dwordx4 v[218:221], v248, s[4:5] nt
	global_load_dwordx4 v[222:225], v248, s[4:5] offset:16 nt
	s_waitcnt vmcnt(24)
; #define PG8_BAR __builtin_amdgcn_s_barrier()
; template <class Epi, class Sched, bool ALIGN_EPI = false, bool SP2 = false>
; __device__ __forceinline__ void gemm_phase(PG8_LAS unsigned char* lds, const Gemm g, const Sched& S, const Epi& E) {
;     ...
;         cur = nxt; cA = nA; cB = nB; ++ui;
;         if constexpr (ALIGN_EPI) { if (wr == 1) PG8_BAR; }
;     __device__ __forceinline__ void operator()(const f32x4 (&acc)[2][2][4][2], const pg8::Unit& u, int wr, int wc, int fr, int fq) const {
;     ...
;                 for (int bj = 0; bj < 2; ++bj) { const size_t idx = (size_t)(row0 + ai * 128 + m * 16) * D + col0 + bj * 128;
;                     const f32x4 a = *(const f32x4*)(X + idx), c = *(const f32x4*)(X + idx + 4);
;                     *(f32x4*)(O + idx) = a + acc[ai][bj][m][0]; *(f32x4*)(O + idx + 4) = c + acc[ai][bj][m][1]; }
	v_pk_add_f32 v[86:87], v[86:87], v[226:227]
	v_pk_add_f32 v[88:89], v[88:89], v[228:229]
	v_pk_add_f32 v[82:83], v[82:83], v[230:231]
	v_pk_add_f32 v[84:85], v[84:85], v[232:233]
	global_store_dwordx4 v170, v[86:89], s[36:37] offset:512
	global_store_dwordx4 v170, v[82:85], s[36:37] offset:528
	global_load_dwordx4 v[226:229], v248, s[4:5] offset:512 nt
	global_load_dwordx4 v[230:233], v248, s[4:5] offset:528 nt
	s_waitcnt vmcnt(26)
	v_pk_add_f32 v[78:79], v[78:79], v[234:235]
	v_pk_add_f32 v[80:81], v[80:81], v[236:237]
	v_pk_add_f32 v[74:75], v[74:75], v[238:239]
	v_pk_add_f32 v[76:77], v[76:77], v[240:241]
	global_store_dwordx4 v171, v[78:81], s[36:37]
	global_store_dwordx4 v171, v[74:77], s[36:37] offset:16
	global_load_dwordx4 v[234:237], v249, s[4:5] nt
	global_load_dwordx4 v[238:241], v249, s[4:5] offset:16 nt
	s_waitcnt vmcnt(28)
	v_pk_add_f32 v[70:71], v[70:71], v[160:161]
	v_pk_add_f32 v[72:73], v[72:73], v[162:163]
	v_pk_add_f32 v[66:67], v[66:67], v[164:165]
	v_pk_add_f32 v[68:69], v[68:69], v[166:167]
	global_store_dwordx4 v171, v[70:73], s[36:37] offset:512
	global_store_dwordx4 v171, v[66:69], s[36:37] offset:528
	global_load_dwordx4 v[160:163], v249, s[4:5] offset:512 nt
	global_load_dwordx4 v[164:167], v249, s[4:5] offset:528 nt
	s_waitcnt vmcnt(28)
	v_pk_add_f32 v[62:63], v[62:63], v[186:187]
	v_pk_add_f32 v[64:65], v[64:65], v[188:189]
	v_pk_add_f32 v[58:59], v[58:59], v[190:191]
	v_pk_add_f32 v[60:61], v[60:61], v[192:193]
	global_store_dwordx4 v246, v[62:65], s[36:37]
	global_store_dwordx4 v246, v[58:61], s[36:37] offset:16
	s_waitcnt vmcnt(26)
	v_pk_add_f32 v[54:55], v[54:55], v[194:195]
	v_pk_add_f32 v[56:57], v[56:57], v[196:197]
	v_pk_add_f32 v[50:51], v[50:51], v[198:199]
	v_pk_add_f32 v[52:53], v[52:53], v[200:201]
	global_store_dwordx4 v246, v[54:57], s[36:37] offset:512
	global_store_dwordx4 v246, v[50:53], s[36:37] offset:528
	s_waitcnt vmcnt(24)
	v_pk_add_f32 v[46:47], v[46:47], v[202:203]
	v_pk_add_f32 v[48:49], v[48:49], v[204:205]
	v_pk_add_f32 v[42:43], v[42:43], v[206:207]
	v_pk_add_f32 v[44:45], v[44:45], v[208:209]
	global_store_dwordx4 v247, v[46:49], s[36:37]
	global_store_dwordx4 v247, v[42:45], s[36:37] offset:16
	s_waitcnt vmcnt(22)
	v_pk_add_f32 v[38:39], v[38:39], v[210:211]
	v_pk_add_f32 v[40:41], v[40:41], v[212:213]
	v_pk_add_f32 v[34:35], v[34:35], v[214:215]
	v_pk_add_f32 v[36:37], v[36:37], v[216:217]
	global_store_dwordx4 v247, v[38:41], s[36:37] offset:512
	global_store_dwordx4 v247, v[34:37], s[36:37] offset:528
	s_waitcnt vmcnt(20)
	v_pk_add_f32 v[30:31], v[30:31], v[218:219]
	v_pk_add_f32 v[32:33], v[32:33], v[220:221]
	v_pk_add_f32 v[26:27], v[26:27], v[222:223]
	v_pk_add_f32 v[28:29], v[28:29], v[224:225]
	global_store_dwordx4 v248, v[30:33], s[36:37]
	global_store_dwordx4 v248, v[26:29], s[36:37] offset:16
	s_waitcnt vmcnt(18)
	v_pk_add_f32 v[22:23], v[22:23], v[226:227]
	v_pk_add_f32 v[24:25], v[24:25], v[228:229]
	v_pk_add_f32 v[18:19], v[18:19], v[230:231]
	v_pk_add_f32 v[20:21], v[20:21], v[232:233]
	global_store_dwordx4 v248, v[22:25], s[36:37] offset:512
	global_store_dwordx4 v248, v[18:21], s[36:37] offset:528
	s_waitcnt vmcnt(16)
	v_pk_add_f32 v[14:15], v[14:15], v[234:235]
	v_pk_add_f32 v[16:17], v[16:17], v[236:237]
	v_pk_add_f32 v[10:11], v[10:11], v[238:239]
	v_pk_add_f32 v[12:13], v[12:13], v[240:241]
	global_store_dwordx4 v249, v[14:17], s[36:37]
	global_store_dwordx4 v249, v[10:13], s[36:37] offset:16
	s_waitcnt vmcnt(14)
	v_pk_add_f32 v[6:7], v[6:7], v[160:161]
	v_pk_add_f32 v[8:9], v[8:9], v[162:163]
	v_pk_add_f32 v[2:3], v[2:3], v[164:165]
	v_pk_add_f32 v[4:5], v[4:5], v[166:167]
	global_store_dwordx4 v249, v[6:9], s[36:37] offset:512
	global_store_dwordx4 v249, v[2:5], s[36:37] offset:528
	s_mov_b64 s[20:21], -1
	s_cbranch_vccnz .LBB0_608
	s_andn2_b64 vcc, exec, s[0:1]
	s_cbranch_vccnz .LBB0_607
	s_barrier
	s_branch .LBB0_607

; template <bool BF> DI void norm_rows4(float* src, const float* gw, bf16* dstb, int r0, int stride, int lane) {
;     f32x4 v[4][4];
; #pragma unroll
;     for (int k = 0; k < 4; ++k) { const int r = r0 + k * stride;
; #pragma unroll
;         for (int j = 0; j < 4; ++j) v[k][j] = r < M ? *(const f32x4*)(src + (size_t)r * D + 4 * lane + 256 * j) : (f32x4){0.f, 0.f, 0.f, 0.f}; }
;     f32x4 gg[4];
; #pragma unroll
;     for (int j = 0; j < 4; ++j) gg[j] = *(const f32x4*)(gw + 4 * lane + 256 * j);
; #pragma unroll
;     for (int k = 0; k < 4; ++k) { const int r = r0 + k * stride; float s = 0.f;
; #pragma unroll
;         for (int j = 0; j < 4; ++j) s += (v[k][j].x * v[k][j].x + v[k][j].y * v[k][j].y) + (v[k][j].z * v[k][j].z + v[k][j].w * v[k][j].w);
;         const float rs = 1.f / sqrtf(wave_sum(s) * (1.f / D) + 1e-6f);
.LBB0_679:
	s_ashr_i32 s1, s0, 31
	s_lshl_b64 s[4:5], s[0:1], 12
	v_lshl_add_u64 v[92:93], v[82:83], 0, s[4:5]
	global_load_dwordx4 v[78:81], v[92:93], off nt
	global_load_dwordx4 v[74:77], v[92:93], off offset:1024 nt
	global_load_dwordx4 v[66:69], v[92:93], off offset:2048 nt
	global_load_dwordx4 v[62:65], v[92:93], off offset:3072 nt
	s_add_i32 s16, s0, s74
	s_cmp_lt_i32 s16, 0x10000
	s_cselect_b64 s[4:5], -1, 0
	s_ashr_i32 s17, s16, 31
	s_lshl_b64 s[6:7], s[16:17], 12
	s_cmp_gt_i32 s16, 0xffff
	v_lshl_add_u64 v[90:91], v[82:83], 0, s[6:7]
	v_mov_b32_e32 v34, 0
	v_mov_b32_e32 v38, 0
	v_mov_b32_e32 v39, 0
	v_mov_b32_e32 v40, 0
	v_mov_b32_e32 v41, 0
	s_cbranch_scc1 .LBB0_681
	global_load_dwordx4 v[38:41], v[90:91], off nt
.LBB0_681:
	v_cndmask_b32_e64 v2, 0, 1, s[4:5]
	v_cmp_ne_u32_e64 s[8:9], 1, v2
	s_andn2_b64 vcc, exec, s[4:5]
	v_mov_b32_e32 v35, 0
	v_mov_b32_e32 v36, 0
	v_mov_b32_e32 v37, 0
	s_cbranch_vccnz .LBB0_683
	global_load_dwordx4 v[34:37], v[90:91], off offset:1024 nt
.LBB0_683:
	v_mov_b32_e32 v42, 0
	s_and_b64 vcc, exec, s[8:9]
	v_mov_b32_e32 v50, 0
	v_mov_b32_e32 v51, 0
	v_mov_b32_e32 v52, 0
	v_mov_b32_e32 v53, 0
	s_cbranch_vccnz .LBB0_685
	global_load_dwordx4 v[50:53], v[90:91], off offset:2048 nt
.LBB0_685:
	s_and_b64 vcc, exec, s[8:9]
	v_mov_b32_e32 v43, 0
	v_mov_b32_e32 v44, 0
	v_mov_b32_e32 v45, 0
	s_cbranch_vccnz .LBB0_687
	global_load_dwordx4 v[42:45], v[90:91], off offset:3072 nt
.LBB0_687:
	v_readlane_b32 s1, v244, 47
	s_add_i32 s6, s1, s0
	s_cmp_lt_i32 s6, 0x10000
	s_cselect_b64 s[4:5], -1, 0
	s_ashr_i32 s7, s6, 31
	s_lshl_b64 s[12:13], s[6:7], 12
	s_cmp_gt_i32 s6, 0xffff
	v_lshl_add_u64 v[88:89], v[82:83], 0, s[12:13]
	v_mov_b32_e32 v18, 0
	v_mov_b32_e32 v22, 0
	v_mov_b32_e32 v23, 0
	v_mov_b32_e32 v24, 0
	v_mov_b32_e32 v25, 0
	s_cbranch_scc1 .LBB0_689
	global_load_dwordx4 v[22:25], v[88:89], off nt
.LBB0_689:
	v_cndmask_b32_e64 v2, 0, 1, s[4:5]
	v_cmp_ne_u32_e64 s[6:7], 1, v2
	s_andn2_b64 vcc, exec, s[4:5]
	s_waitcnt lgkmcnt(0)
	v_mov_b32_e32 v19, 0
	v_mov_b32_e32 v20, 0
	v_mov_b32_e32 v21, 0
	s_cbranch_vccnz .LBB0_691
	global_load_dwordx4 v[18:21], v[88:89], off offset:1024 nt
.LBB0_691:
	v_mov_b32_e32 v26, 0
	s_and_b64 vcc, exec, s[6:7]
	v_mov_b32_e32 v30, 0
	v_mov_b32_e32 v31, 0
	v_mov_b32_e32 v32, 0
	v_mov_b32_e32 v33, 0
	s_cbranch_vccnz .LBB0_693
	global_load_dwordx4 v[30:33], v[88:89], off offset:2048 nt
.LBB0_693:
	s_and_b64 vcc, exec, s[6:7]
	v_mov_b32_e32 v27, 0
	v_mov_b32_e32 v28, 0
	v_mov_b32_e32 v29, 0
	s_cbranch_vccnz .LBB0_695
	global_load_dwordx4 v[26:29], v[88:89], off offset:3072 nt
.LBB0_695:
	v_readlane_b32 s1, v245, 41
	s_add_i32 s4, s1, s0
	s_cmp_lt_i32 s4, 0x10000
	s_cselect_b64 s[0:1], -1, 0
	s_ashr_i32 s5, s4, 31
	s_lshl_b64 s[12:13], s[4:5], 12
	s_cmp_gt_i32 s4, 0xffff
	v_lshl_add_u64 v[86:87], v[82:83], 0, s[12:13]
	v_mov_b32_e32 v2, 0
	v_mov_b32_e32 v6, 0
	v_mov_b32_e32 v7, 0
	v_mov_b32_e32 v8, 0
	v_mov_b32_e32 v9, 0
	s_cbranch_scc1 .LBB0_697
	global_load_dwordx4 v[6:9], v[86:87], off nt
.LBB0_697:
	v_cndmask_b32_e64 v3, 0, 1, s[0:1]
	v_cmp_ne_u32_e64 s[4:5], 1, v3
	s_andn2_b64 vcc, exec, s[0:1]
	v_mov_b32_e32 v3, 0
	v_mov_b32_e32 v4, 0
	v_mov_b32_e32 v5, 0
	s_cbranch_vccnz .LBB0_699
	global_load_dwordx4 v[2:5], v[86:87], off offset:1024 nt
.LBB0_699:
	v_mov_b32_e32 v10, 0
	s_and_b64 vcc, exec, s[4:5]
	v_mov_b32_e32 v14, 0
	v_mov_b32_e32 v15, 0
	v_mov_b32_e32 v16, 0
	v_mov_b32_e32 v17, 0
	s_cbranch_vccnz .LBB0_701
	global_load_dwordx4 v[14:17], v[86:87], off offset:2048 nt
.LBB0_701:
	s_and_b64 vcc, exec, s[4:5]
	v_mov_b32_e32 v11, 0
	v_mov_b32_e32 v12, 0
	v_mov_b32_e32 v13, 0
	s_cbranch_vccnz .LBB0_703
	global_load_dwordx4 v[10:13], v[86:87], off offset:3072 nt
.LBB0_703:
	s_waitcnt vmcnt(3)
	v_pk_mul_f32 v[46:47], v[80:81], v[80:81]
	v_pk_mul_f32 v[48:49], v[78:79], v[78:79]
	global_load_dwordx4 v[70:73], v[84:85], off nt
	global_load_dwordx4 v[58:61], v[84:85], off offset:1024 nt
	v_pk_mov_b32 v[54:55], v[48:49], v[46:47] op_sel:[1,0]
	v_mov_b32_e32 v49, v47
	v_pk_add_f32 v[46:47], v[54:55], v[48:49]
	s_waitcnt vmcnt(4)
	v_pk_mul_f32 v[48:49], v[76:77], v[76:77]
	v_pk_mul_f32 v[54:55], v[74:75], v[74:75]
	v_pk_add_f32 v[46:47], v[46:47], v[46:47] op_sel:[0,1] op_sel_hi:[1,0]
	v_pk_mov_b32 v[56:57], v[54:55], v[48:49] op_sel:[1,0]
	v_mov_b32_e32 v55, v49
	v_pk_add_f32 v[48:49], v[56:57], v[54:55]
	s_waitcnt vmcnt(2)
	v_mul_f32_e32 v54, v62, v62
	v_mul_f32_e32 v55, v63, v63
	v_pk_add_f32 v[48:49], v[48:49], v[48:49] op_sel:[0,1] op_sel_hi:[1,0]
	v_mov_b32_e32 v47, v54
	v_mov_b32_e32 v49, v55
	v_pk_add_f32 v[46:47], v[46:47], v[48:49]
	v_mul_f32_e32 v48, v67, v67
	v_mul_f32_e32 v54, v69, v69
	v_mul_f32_e32 v56, v64, v64
	v_mul_f32_e32 v57, v65, v65
	v_pk_fma_f32 v[48:49], v[66:67], v[66:67], v[48:49] op_sel_hi:[1,1,0]
	v_pk_fma_f32 v[54:55], v[68:69], v[68:69], v[54:55] op_sel_hi:[1,1,0]
	v_mov_b32_e32 v49, v56
	v_mov_b32_e32 v55, v57
	v_pk_add_f32 v[48:49], v[48:49], v[54:55]
	global_load_dwordx4 v[54:57], v[84:85], off offset:2048 nt
	v_pk_add_f32 v[46:47], v[46:47], v[48:49]
	v_mul_f32_e32 v106, v37, v37
	v_add_f32_e32 v46, v46, v47
	ds_bpermute_b32 v47, v0, v46
	v_fmac_f32_e32 v106, v36, v36
	s_waitcnt lgkmcnt(0)
	v_add_f32_e32 v46, v46, v47
	ds_bpermute_b32 v47, v95, v46
	s_waitcnt lgkmcnt(0)
	v_add_f32_e32 v46, v46, v47
	ds_bpermute_b32 v47, v96, v46
	s_waitcnt lgkmcnt(0)
	v_add_f32_e32 v46, v46, v47
	ds_bpermute_b32 v47, v97, v46
	s_waitcnt lgkmcnt(0)
	v_add_f32_e32 v46, v46, v47
	ds_bpermute_b32 v47, v98, v46
	s_waitcnt lgkmcnt(0)
	v_add_f32_e32 v46, v46, v47
	ds_bpermute_b32 v47, v99, v46
	s_waitcnt lgkmcnt(0)
; DI unsigned cvtpk(float lo, float hi) { f32x2_t v = {lo, hi}; bf16x2_t b = __builtin_convertvector(v, bf16x2_t); return __builtin_bit_cast(unsigned, b); }
; template <bool BF> DI void norm_rows4(float* src, const float* gw, bf16* dstb, int r0, int stride, int lane) {
;     ...
;     for (int k = 0; k < 4; ++k) { const int r = r0 + k * stride; float s = 0.f;
; #pragma unroll
;         for (int j = 0; j < 4; ++j) s += (v[k][j].x * v[k][j].x + v[k][j].y * v[k][j].y) + (v[k][j].z * v[k][j].z + v[k][j].w * v[k][j].w);
;         const float rs = 1.f / sqrtf(wave_sum(s) * (1.f / D) + 1e-6f);
;         if (r < M) {
; #pragma unroll
;             for (int j = 0; j < 4; ++j) {
;                 const f32x4 y = (f32x4){v[k][j].x * rs * gg[j].x, v[k][j].y * rs * gg[j].y, v[k][j].z * rs * gg[j].z, v[k][j].w * rs * gg[j].w};
;                 if (BF) { u32x2 w; w.x = cvtpk(y.x, y.y); w.y = cvtpk(y.z, y.w); *(u32x2*)(dstb + (size_t)r * D + 4 * lane + 256 * j) = w; }
;                 else *(f32x4*)(src + (size_t)r * D + 4 * lane + 256 * j) = y;
;             }
;         }
;     }
	v_add_f32_e32 v46, v46, v47
	v_fmamk_f32 v46, v46, 0x3a800000, v178
	v_mul_f32_e32 v47, 0x4f800000, v46
	v_cmp_gt_f32_e32 vcc, s62, v46
	s_nop 1
	v_cndmask_b32_e32 v100, v46, v47, vcc
	global_load_dwordx4 v[46:49], v[84:85], off offset:3072 nt
	v_sqrt_f32_e32 v101, v100
	s_nop 0
	v_add_u32_e32 v102, -1, v101
	v_fma_f32 v104, -v102, v101, v100
	v_add_u32_e32 v103, 1, v101
	v_cmp_ge_f32_e64 s[0:1], 0, v104
	s_nop 1
	v_cndmask_b32_e64 v102, v101, v102, s[0:1]
	v_fma_f32 v101, -v103, v101, v100
	v_cmp_lt_f32_e64 s[0:1], 0, v101
	s_nop 1
	v_cndmask_b32_e64 v101, v102, v103, s[0:1]
	v_mul_f32_e32 v102, 0x37800000, v101
	v_cndmask_b32_e32 v101, v101, v102, vcc
	v_cmp_class_f32_e32 vcc, v100, v179
	s_nop 1
	v_cndmask_b32_e32 v100, v101, v100, vcc
	v_div_scale_f32 v101, s[0:1], v100, v100, 1.0
	v_rcp_f32_e32 v102, v101
	s_nop 0
	v_fma_f32 v103, -v101, v102, 1.0
	v_fmac_f32_e32 v102, v103, v102
	v_div_scale_f32 v103, vcc, 1.0, v100, 1.0
	v_mul_f32_e32 v104, v103, v102
	v_fma_f32 v105, -v101, v104, v103
	v_fmac_f32_e32 v104, v105, v102
	v_fma_f32 v101, -v101, v104, v103
	v_mul_f32_e32 v103, v39, v39
	v_mul_f32_e32 v105, v41, v41
	v_fmac_f32_e32 v103, v38, v38
	v_fmac_f32_e32 v105, v40, v40
	v_add_f32_e32 v103, v103, v105
	v_mul_f32_e32 v105, v35, v35
	v_fmac_f32_e32 v105, v34, v34
	v_add_f32_e32 v105, v105, v106
	v_add_f32_e32 v103, v103, v105
	v_mul_f32_e32 v105, v51, v51
	v_mul_f32_e32 v106, v53, v53
	v_fmac_f32_e32 v105, v50, v50
	v_fmac_f32_e32 v106, v52, v52
	v_add_f32_e32 v105, v105, v106
	v_add_f32_e32 v103, v103, v105
	v_mul_f32_e32 v105, v43, v43
	v_mul_f32_e32 v106, v45, v45
	v_fmac_f32_e32 v105, v42, v42
	v_fmac_f32_e32 v106, v44, v44
	v_add_f32_e32 v105, v105, v106
	v_add_f32_e32 v103, v103, v105
	ds_bpermute_b32 v105, v0, v103
	v_div_fmas_f32 v101, v101, v102, v104
	v_div_fixup_f32 v100, v101, v100, 1.0
	v_pk_mul_f32 v[78:79], v[78:79], v[100:101] op_sel_hi:[1,0]
	s_and_b64 vcc, exec, s[8:9]
	s_waitcnt lgkmcnt(0)
	v_add_f32_e32 v101, v103, v105
	ds_bpermute_b32 v102, v95, v101
	v_pk_mul_f32 v[80:81], v[80:81], v[100:101] op_sel_hi:[1,0]
	s_waitcnt vmcnt(3)
	v_pk_mul_f32 v[78:79], v[70:71], v[78:79]
	v_pk_mul_f32 v[80:81], v[72:73], v[80:81]
	global_store_dwordx4 v[92:93], v[78:81], off nt
	v_pk_mul_f32 v[74:75], v[74:75], v[100:101] op_sel_hi:[1,0]
	v_pk_mul_f32 v[76:77], v[76:77], v[100:101] op_sel_hi:[1,0]
	s_waitcnt lgkmcnt(0)
	v_add_f32_e32 v78, v101, v102
	ds_bpermute_b32 v79, v96, v78
	s_waitcnt vmcnt(3)
	v_pk_mul_f32 v[76:77], v[60:61], v[76:77]
	v_pk_mul_f32 v[74:75], v[58:59], v[74:75]
	global_store_dwordx4 v[92:93], v[74:77], off offset:1024 nt
	v_pk_mul_f32 v[66:67], v[66:67], v[100:101] op_sel_hi:[1,0]
	s_waitcnt lgkmcnt(0)
	v_add_f32_e32 v78, v78, v79
	ds_bpermute_b32 v79, v97, v78
	v_pk_mul_f32 v[68:69], v[68:69], v[100:101] op_sel_hi:[1,0]
	s_waitcnt vmcnt(3)
	v_pk_mul_f32 v[66:67], v[54:55], v[66:67]
	v_pk_mul_f32 v[68:69], v[56:57], v[68:69]
	global_store_dwordx4 v[92:93], v[66:69], off offset:2048 nt
	s_waitcnt lgkmcnt(0)
	v_add_f32_e32 v74, v78, v79
	ds_bpermute_b32 v75, v98, v74
	v_pk_mul_f32 v[68:69], v[62:63], v[100:101] op_sel_hi:[1,0]
	v_pk_mul_f32 v[64:65], v[64:65], v[100:101] op_sel_hi:[1,0]
	s_waitcnt lgkmcnt(0)
	v_add_f32_e32 v62, v74, v75
	ds_bpermute_b32 v63, v99, v62
	s_waitcnt vmcnt(3)
	v_pk_mul_f32 v[66:67], v[48:49], v[64:65]
	v_pk_mul_f32 v[64:65], v[46:47], v[68:69]
	global_store_dwordx4 v[92:93], v[64:67], off offset:3072 nt
	s_cbranch_vccnz .LBB0_705
	s_waitcnt lgkmcnt(0)
	v_add_f32_e32 v62, v62, v63
	v_fmamk_f32 v62, v62, 0x3a800000, v178
	v_mul_f32_e32 v63, 0x4f800000, v62
	v_cmp_gt_f32_e32 vcc, s62, v62
	s_nop 1
	v_cndmask_b32_e32 v62, v62, v63, vcc
	v_sqrt_f32_e32 v63, v62
	s_nop 0
	v_add_u32_e32 v64, -1, v63
	v_fma_f32 v66, -v64, v63, v62
	v_add_u32_e32 v65, 1, v63
	v_cmp_ge_f32_e64 s[0:1], 0, v66
	s_nop 1
	v_cndmask_b32_e64 v64, v63, v64, s[0:1]
	v_fma_f32 v63, -v65, v63, v62
	v_cmp_lt_f32_e64 s[0:1], 0, v63
	s_nop 1
	v_cndmask_b32_e64 v63, v64, v65, s[0:1]
	v_mul_f32_e32 v64, 0x37800000, v63
	v_cndmask_b32_e32 v63, v63, v64, vcc
	v_cmp_class_f32_e32 vcc, v62, v179
	s_nop 1
	v_cndmask_b32_e32 v62, v63, v62, vcc
	v_div_scale_f32 v63, s[0:1], v62, v62, 1.0
	v_rcp_f32_e32 v64, v63
	s_nop 0
	v_fma_f32 v65, -v63, v64, 1.0
	v_fmac_f32_e32 v64, v65, v64
	v_div_scale_f32 v65, vcc, 1.0, v62, 1.0
	v_mul_f32_e32 v66, v65, v64
	v_fma_f32 v67, -v63, v66, v65
	v_fmac_f32_e32 v66, v67, v64
	v_fma_f32 v63, -v63, v66, v65
	v_div_fmas_f32 v63, v63, v64, v66
	v_div_fixup_f32 v62, v63, v62, 1.0
	v_pk_mul_f32 v[34:35], v[34:35], v[62:63] op_sel_hi:[1,0]
	v_pk_mul_f32 v[36:37], v[36:37], v[62:63] op_sel_hi:[1,0]
	v_pk_mul_f32 v[34:35], v[58:59], v[34:35]
	v_pk_mul_f32 v[36:37], v[60:61], v[36:37]
	global_store_dwordx4 v[90:91], v[34:37], off offset:1024 nt
	v_pk_mul_f32 v[38:39], v[38:39], v[62:63] op_sel_hi:[1,0]
	v_pk_mul_f32 v[40:41], v[40:41], v[62:63] op_sel_hi:[1,0]
	v_pk_mul_f32 v[34:35], v[50:51], v[62:63] op_sel_hi:[1,0]
	v_pk_mul_f32 v[36:37], v[52:53], v[62:63] op_sel_hi:[1,0]
	v_pk_mul_f32 v[34:35], v[54:55], v[34:35]
	v_pk_mul_f32 v[36:37], v[56:57], v[36:37]
	global_store_dwordx4 v[90:91], v[34:37], off offset:2048 nt
	v_pk_mul_f32 v[40:41], v[72:73], v[40:41]
	v_pk_mul_f32 v[38:39], v[70:71], v[38:39]
	v_pk_mul_f32 v[34:35], v[42:43], v[62:63] op_sel_hi:[1,0]
	v_pk_mul_f32 v[36:37], v[44:45], v[62:63] op_sel_hi:[1,0]
	v_pk_mul_f32 v[34:35], v[46:47], v[34:35]
	v_pk_mul_f32 v[36:37], v[48:49], v[36:37]
	global_store_dwordx4 v[90:91], v[38:41], off nt
	global_store_dwordx4 v[90:91], v[34:37], off offset:3072 nt
; DI unsigned cvtpk(float lo, float hi) { f32x2_t v = {lo, hi}; bf16x2_t b = __builtin_convertvector(v, bf16x2_t); return __builtin_bit_cast(unsigned, b); }
; template <bool BF> DI void norm_rows4(float* src, const float* gw, bf16* dstb, int r0, int stride, int lane) {
;     ...
;     for (int k = 0; k < 4; ++k) { const int r = r0 + k * stride; float s = 0.f;
; #pragma unroll
;         for (int j = 0; j < 4; ++j) s += (v[k][j].x * v[k][j].x + v[k][j].y * v[k][j].y) + (v[k][j].z * v[k][j].z + v[k][j].w * v[k][j].w);
;         const float rs = 1.f / sqrtf(wave_sum(s) * (1.f / D) + 1e-6f);
;         if (r < M) {
; #pragma unroll
;             for (int j = 0; j < 4; ++j) {
;                 const f32x4 y = (f32x4){v[k][j].x * rs * gg[j].x, v[k][j].y * rs * gg[j].y, v[k][j].z * rs * gg[j].z, v[k][j].w * rs * gg[j].w};
;                 if (BF) { u32x2 w; w.x = cvtpk(y.x, y.y); w.y = cvtpk(y.z, y.w); *(u32x2*)(dstb + (size_t)r * D + 4 * lane + 256 * j) = w; }
;                 else *(f32x4*)(src + (size_t)r * D + 4 * lane + 256 * j) = y;
;             }
;         }
;     }
.LBB0_705:
	s_nop 1
	v_mul_f32_e32 v34, v23, v23
	v_mul_f32_e32 v35, v25, v25
	v_fmac_f32_e32 v34, v22, v22
	v_fmac_f32_e32 v35, v24, v24
	v_add_f32_e32 v34, v34, v35
	v_mul_f32_e32 v35, v19, v19
	v_mul_f32_e32 v36, v21, v21
	v_fmac_f32_e32 v35, v18, v18
	v_fmac_f32_e32 v36, v20, v20
	v_add_f32_e32 v35, v35, v36
	v_add_f32_e32 v34, v34, v35
	v_mul_f32_e32 v35, v31, v31
	v_mul_f32_e32 v36, v33, v33
	v_fmac_f32_e32 v35, v30, v30
	v_fmac_f32_e32 v36, v32, v32
	v_add_f32_e32 v35, v35, v36
	v_add_f32_e32 v34, v34, v35
	v_mul_f32_e32 v35, v27, v27
	v_mul_f32_e32 v36, v29, v29
	v_fmac_f32_e32 v35, v26, v26
	v_fmac_f32_e32 v36, v28, v28
	v_add_f32_e32 v35, v35, v36
	v_add_f32_e32 v34, v34, v35
	ds_bpermute_b32 v35, v0, v34
	s_and_b64 vcc, exec, s[6:7]
	s_waitcnt lgkmcnt(0)
	v_add_f32_e32 v34, v34, v35
	ds_bpermute_b32 v35, v95, v34
	s_waitcnt lgkmcnt(0)
	v_add_f32_e32 v34, v34, v35
	ds_bpermute_b32 v35, v96, v34
	s_waitcnt lgkmcnt(0)
	v_add_f32_e32 v34, v34, v35
	ds_bpermute_b32 v35, v97, v34
	s_waitcnt lgkmcnt(0)
	v_add_f32_e32 v34, v34, v35
	ds_bpermute_b32 v35, v98, v34
	s_waitcnt lgkmcnt(0)
	v_add_f32_e32 v34, v34, v35
	ds_bpermute_b32 v35, v99, v34
	s_cbranch_vccnz .LBB0_707
	s_waitcnt lgkmcnt(0)
	v_add_f32_e32 v34, v34, v35
	v_fmamk_f32 v34, v34, 0x3a800000, v178
	v_mul_f32_e32 v35, 0x4f800000, v34
	v_cmp_gt_f32_e32 vcc, s62, v34
	s_nop 1
	v_cndmask_b32_e32 v34, v34, v35, vcc
	v_sqrt_f32_e32 v35, v34
	s_nop 0
	v_add_u32_e32 v36, -1, v35
	v_fma_f32 v38, -v36, v35, v34
	v_add_u32_e32 v37, 1, v35
	v_cmp_ge_f32_e64 s[0:1], 0, v38
	s_nop 1
	v_cndmask_b32_e64 v36, v35, v36, s[0:1]
	v_fma_f32 v35, -v37, v35, v34
	v_cmp_lt_f32_e64 s[0:1], 0, v35
	s_nop 1
	v_cndmask_b32_e64 v35, v36, v37, s[0:1]
	v_mul_f32_e32 v36, 0x37800000, v35
	v_cndmask_b32_e32 v35, v35, v36, vcc
	v_cmp_class_f32_e32 vcc, v34, v179
	s_nop 1
	v_cndmask_b32_e32 v34, v35, v34, vcc
	v_div_scale_f32 v35, s[0:1], v34, v34, 1.0
	v_rcp_f32_e32 v36, v35
	s_nop 0
	v_fma_f32 v37, -v35, v36, 1.0
	v_fmac_f32_e32 v36, v37, v36
	v_div_scale_f32 v37, vcc, 1.0, v34, 1.0
	v_mul_f32_e32 v38, v37, v36
	v_fma_f32 v39, -v35, v38, v37
	v_fmac_f32_e32 v38, v39, v36
	v_fma_f32 v35, -v35, v38, v37
	v_div_fmas_f32 v35, v35, v36, v38
	v_div_fixup_f32 v34, v35, v34, 1.0
	v_pk_mul_f32 v[18:19], v[18:19], v[34:35] op_sel_hi:[1,0]
	v_pk_mul_f32 v[20:21], v[20:21], v[34:35] op_sel_hi:[1,0]
	v_pk_mul_f32 v[18:19], v[58:59], v[18:19]
	v_pk_mul_f32 v[20:21], v[60:61], v[20:21]
	global_store_dwordx4 v[88:89], v[18:21], off offset:1024 nt
	v_pk_mul_f32 v[22:23], v[22:23], v[34:35] op_sel_hi:[1,0]
	v_pk_mul_f32 v[24:25], v[24:25], v[34:35] op_sel_hi:[1,0]
	v_pk_mul_f32 v[18:19], v[30:31], v[34:35] op_sel_hi:[1,0]
	v_pk_mul_f32 v[20:21], v[32:33], v[34:35] op_sel_hi:[1,0]
	v_pk_mul_f32 v[18:19], v[54:55], v[18:19]
	v_pk_mul_f32 v[20:21], v[56:57], v[20:21]
	global_store_dwordx4 v[88:89], v[18:21], off offset:2048 nt
	v_pk_mul_f32 v[24:25], v[72:73], v[24:25]
	v_pk_mul_f32 v[22:23], v[70:71], v[22:23]
	v_pk_mul_f32 v[18:19], v[26:27], v[34:35] op_sel_hi:[1,0]
	v_pk_mul_f32 v[20:21], v[28:29], v[34:35] op_sel_hi:[1,0]
	v_pk_mul_f32 v[18:19], v[46:47], v[18:19]
	v_pk_mul_f32 v[20:21], v[48:49], v[20:21]
	global_store_dwordx4 v[88:89], v[22:25], off nt
	global_store_dwordx4 v[88:89], v[18:21], off offset:3072 nt
.LBB0_707:
	s_nop 1
	v_mul_f32_e32 v18, v7, v7
	v_mul_f32_e32 v19, v9, v9
	v_fmac_f32_e32 v18, v6, v6
	v_fmac_f32_e32 v19, v8, v8
	v_add_f32_e32 v18, v18, v19
	v_mul_f32_e32 v19, v3, v3
	v_mul_f32_e32 v20, v5, v5
	v_fmac_f32_e32 v19, v2, v2
	v_fmac_f32_e32 v20, v4, v4
	v_add_f32_e32 v19, v19, v20
	v_add_f32_e32 v18, v18, v19
	v_mul_f32_e32 v19, v15, v15
	v_mul_f32_e32 v20, v17, v17
	v_fmac_f32_e32 v19, v14, v14
	v_fmac_f32_e32 v20, v16, v16
	v_add_f32_e32 v19, v19, v20
	v_add_f32_e32 v18, v18, v19
	v_mul_f32_e32 v19, v11, v11
	v_mul_f32_e32 v20, v13, v13
	v_fmac_f32_e32 v19, v10, v10
	v_fmac_f32_e32 v20, v12, v12
	v_add_f32_e32 v19, v19, v20
	v_add_f32_e32 v18, v18, v19
	ds_bpermute_b32 v19, v0, v18
	s_and_b64 vcc, exec, s[4:5]
	s_waitcnt lgkmcnt(0)
	v_add_f32_e32 v18, v18, v19
	ds_bpermute_b32 v19, v95, v18
	s_waitcnt lgkmcnt(0)
	v_add_f32_e32 v18, v18, v19
	ds_bpermute_b32 v19, v96, v18
	s_waitcnt lgkmcnt(0)
	v_add_f32_e32 v18, v18, v19
	ds_bpermute_b32 v19, v97, v18
	s_waitcnt lgkmcnt(0)
	v_add_f32_e32 v18, v18, v19
	ds_bpermute_b32 v19, v98, v18
	s_waitcnt lgkmcnt(0)
	v_add_f32_e32 v18, v18, v19
	ds_bpermute_b32 v19, v99, v18
	s_cbranch_vccnz .LBB0_678
	s_waitcnt lgkmcnt(0)
	v_add_f32_e32 v18, v18, v19
	v_fmamk_f32 v18, v18, 0x3a800000, v178
	v_mul_f32_e32 v19, 0x4f800000, v18
	v_cmp_gt_f32_e32 vcc, s62, v18
	s_nop 1
	v_cndmask_b32_e32 v18, v18, v19, vcc
	v_sqrt_f32_e32 v19, v18
	s_nop 0
	v_add_u32_e32 v20, -1, v19
	v_fma_f32 v22, -v20, v19, v18
	v_add_u32_e32 v21, 1, v19
	v_cmp_ge_f32_e64 s[0:1], 0, v22
	s_nop 1
	v_cndmask_b32_e64 v20, v19, v20, s[0:1]
	v_fma_f32 v19, -v21, v19, v18
	v_cmp_lt_f32_e64 s[0:1], 0, v19
	s_nop 1
	v_cndmask_b32_e64 v19, v20, v21, s[0:1]
	v_mul_f32_e32 v20, 0x37800000, v19
	v_cndmask_b32_e32 v19, v19, v20, vcc
	v_cmp_class_f32_e32 vcc, v18, v179
	s_nop 1
	v_cndmask_b32_e32 v18, v19, v18, vcc
	v_div_scale_f32 v19, s[0:1], v18, v18, 1.0
	v_rcp_f32_e32 v20, v19
	s_nop 0
	v_fma_f32 v21, -v19, v20, 1.0
	v_fmac_f32_e32 v20, v21, v20
	v_div_scale_f32 v21, vcc, 1.0, v18, 1.0
	v_mul_f32_e32 v22, v21, v20
	v_fma_f32 v23, -v19, v22, v21
	v_fmac_f32_e32 v22, v23, v20
	v_fma_f32 v19, -v19, v22, v21
	v_div_fmas_f32 v19, v19, v20, v22
	v_div_fixup_f32 v18, v19, v18, 1.0
	v_pk_mul_f32 v[2:3], v[2:3], v[18:19] op_sel_hi:[1,0]
	v_pk_mul_f32 v[4:5], v[4:5], v[18:19] op_sel_hi:[1,0]
	v_pk_mul_f32 v[2:3], v[58:59], v[2:3]
	v_pk_mul_f32 v[4:5], v[60:61], v[4:5]
	global_store_dwordx4 v[86:87], v[2:5], off offset:1024 nt
	v_pk_mul_f32 v[6:7], v[6:7], v[18:19] op_sel_hi:[1,0]
	v_pk_mul_f32 v[8:9], v[8:9], v[18:19] op_sel_hi:[1,0]
	v_pk_mul_f32 v[2:3], v[14:15], v[18:19] op_sel_hi:[1,0]
	v_pk_mul_f32 v[4:5], v[16:17], v[18:19] op_sel_hi:[1,0]
	v_pk_mul_f32 v[2:3], v[54:55], v[2:3]
	v_pk_mul_f32 v[4:5], v[56:57], v[4:5]
	global_store_dwordx4 v[86:87], v[2:5], off offset:2048 nt
	v_pk_mul_f32 v[8:9], v[72:73], v[8:9]
	v_pk_mul_f32 v[6:7], v[70:71], v[6:7]
	v_pk_mul_f32 v[2:3], v[10:11], v[18:19] op_sel_hi:[1,0]
	v_pk_mul_f32 v[4:5], v[12:13], v[18:19] op_sel_hi:[1,0]
	v_pk_mul_f32 v[2:3], v[46:47], v[2:3]
	v_pk_mul_f32 v[4:5], v[48:49], v[4:5]
	global_store_dwordx4 v[86:87], v[6:9], off nt
	global_store_dwordx4 v[86:87], v[2:5], off offset:3072 nt
	s_branch .LBB0_678

; template <bool BF> DI void norm_rows4(float* src, const float* gw, bf16* dstb, int r0, int stride, int lane) {
;     f32x4 v[4][4];
; #pragma unroll
;     for (int k = 0; k < 4; ++k) { const int r = r0 + k * stride;
; #pragma unroll
;         for (int j = 0; j < 4; ++j) v[k][j] = r < M ? *(const f32x4*)(src + (size_t)r * D + 4 * lane + 256 * j) : (f32x4){0.f, 0.f, 0.f, 0.f}; }
;     f32x4 gg[4];
; #pragma unroll
;     for (int j = 0; j < 4; ++j) gg[j] = *(const f32x4*)(gw + 4 * lane + 256 * j);
; #pragma unroll
;     for (int k = 0; k < 4; ++k) { const int r = r0 + k * stride; float s = 0.f;
; #pragma unroll
;         for (int j = 0; j < 4; ++j) s += (v[k][j].x * v[k][j].x + v[k][j].y * v[k][j].y) + (v[k][j].z * v[k][j].z + v[k][j].w * v[k][j].w);
;         const float rs = 1.f / sqrtf(wave_sum(s) * (1.f / D) + 1e-6f);
.LBB0_714:
	s_ashr_i32 s15, s14, 31
	s_lshl_b64 s[0:1], s[14:15], 12
	v_lshl_add_u64 v[2:3], v[82:83], 0, s[0:1]
	global_load_dwordx4 v[78:81], v[2:3], off nt
	global_load_dwordx4 v[74:77], v[2:3], off offset:1024 nt
	global_load_dwordx4 v[70:73], v[2:3], off offset:2048 nt
	global_load_dwordx4 v[66:69], v[2:3], off offset:3072 nt
	s_add_i32 s8, s14, s74
	s_cmp_lt_i32 s8, 0x10000
	s_cselect_b64 s[0:1], -1, 0
	s_ashr_i32 s9, s8, 31
	s_lshl_b64 s[2:3], s[8:9], 12
	s_cmp_gt_i32 s8, 0xffff
	v_lshl_add_u64 v[2:3], v[82:83], 0, s[2:3]
	v_mov_b32_e32 v34, 0
	v_mov_b32_e32 v38, 0
	v_mov_b32_e32 v39, 0
	v_mov_b32_e32 v40, 0
	v_mov_b32_e32 v41, 0
	s_cbranch_scc1 .LBB0_716
	global_load_dwordx4 v[38:41], v[2:3], off nt
.LBB0_716:
	v_cndmask_b32_e64 v0, 0, 1, s[0:1]
	v_cmp_ne_u32_e64 s[6:7], 1, v0
	s_andn2_b64 vcc, exec, s[0:1]
	v_mov_b32_e32 v35, 0
	v_mov_b32_e32 v36, 0
	v_mov_b32_e32 v37, 0
	s_cbranch_vccnz .LBB0_718
	global_load_dwordx4 v[34:37], v[2:3], off offset:1024 nt
.LBB0_718:
	v_mov_b32_e32 v46, 0
	s_and_b64 vcc, exec, s[6:7]
	v_mov_b32_e32 v50, 0
	v_mov_b32_e32 v51, 0
	v_mov_b32_e32 v52, 0
	v_mov_b32_e32 v53, 0
	s_cbranch_vccnz .LBB0_720
	global_load_dwordx4 v[50:53], v[2:3], off offset:2048 nt
.LBB0_720:
	s_and_b64 vcc, exec, s[6:7]
	v_mov_b32_e32 v47, 0
	v_mov_b32_e32 v48, 0
	v_mov_b32_e32 v49, 0
	s_cbranch_vccnz .LBB0_722
	global_load_dwordx4 v[46:49], v[2:3], off offset:3072 nt
.LBB0_722:
	v_readlane_b32 s0, v244, 47
	s_add_i32 s18, s0, s14
	s_cmp_lt_i32 s18, 0x10000
	s_cselect_b64 s[0:1], -1, 0
	s_ashr_i32 s19, s18, 31
	s_lshl_b64 s[2:3], s[18:19], 12
	s_cmp_gt_i32 s18, 0xffff
	v_lshl_add_u64 v[2:3], v[82:83], 0, s[2:3]
	s_waitcnt lgkmcnt(0)
	v_mov_b32_e32 v18, 0
	v_mov_b32_e32 v22, 0
	v_mov_b32_e32 v23, 0
	v_mov_b32_e32 v24, 0
	v_mov_b32_e32 v25, 0
	s_cbranch_scc1 .LBB0_724
	global_load_dwordx4 v[22:25], v[2:3], off nt
.LBB0_724:
	v_cndmask_b32_e64 v0, 0, 1, s[0:1]
	v_cmp_ne_u32_e64 s[4:5], 1, v0
	s_andn2_b64 vcc, exec, s[0:1]
	s_waitcnt lgkmcnt(0)
	v_mov_b32_e32 v19, 0
	v_mov_b32_e32 v20, 0
	v_mov_b32_e32 v21, 0
	s_cbranch_vccnz .LBB0_726
	global_load_dwordx4 v[18:21], v[2:3], off offset:1024 nt
.LBB0_726:
	v_mov_b32_e32 v26, 0
	s_and_b64 vcc, exec, s[4:5]
	v_mov_b32_e32 v30, 0
	v_mov_b32_e32 v31, 0
	v_mov_b32_e32 v32, 0
	v_mov_b32_e32 v33, 0
	s_cbranch_vccnz .LBB0_728
	global_load_dwordx4 v[30:33], v[2:3], off offset:2048 nt
.LBB0_728:
	s_and_b64 vcc, exec, s[4:5]
	v_mov_b32_e32 v27, 0
	v_mov_b32_e32 v28, 0
	v_mov_b32_e32 v29, 0
	s_cbranch_vccnz .LBB0_730
	global_load_dwordx4 v[26:29], v[2:3], off offset:3072 nt
.LBB0_730:
	v_readlane_b32 s0, v245, 41
	s_add_i32 s16, s0, s14
	s_cmp_lt_i32 s16, 0x10000
	s_cselect_b64 s[0:1], -1, 0
	s_ashr_i32 s17, s16, 31
	s_lshl_b64 s[2:3], s[16:17], 12
	s_cmp_gt_i32 s16, 0xffff
	v_lshl_add_u64 v[42:43], v[82:83], 0, s[2:3]
	v_mov_b32_e32 v2, 0
	v_mov_b32_e32 v6, 0
	v_mov_b32_e32 v7, 0
	v_mov_b32_e32 v8, 0
	v_mov_b32_e32 v9, 0
	s_cbranch_scc1 .LBB0_732
	global_load_dwordx4 v[6:9], v[42:43], off nt
.LBB0_732:
	v_cndmask_b32_e64 v0, 0, 1, s[0:1]
	v_cmp_ne_u32_e64 s[2:3], 1, v0
	s_andn2_b64 vcc, exec, s[0:1]
	v_mov_b32_e32 v3, 0
	v_mov_b32_e32 v4, 0
	v_mov_b32_e32 v5, 0
	s_cbranch_vccnz .LBB0_734
	global_load_dwordx4 v[2:5], v[42:43], off offset:1024 nt
.LBB0_734:
	v_mov_b32_e32 v10, 0
	s_and_b64 vcc, exec, s[2:3]
	v_mov_b32_e32 v14, 0
	v_mov_b32_e32 v15, 0
	v_mov_b32_e32 v16, 0
	v_mov_b32_e32 v17, 0
	s_cbranch_vccnz .LBB0_736
	global_load_dwordx4 v[14:17], v[42:43], off offset:2048 nt
.LBB0_736:
	s_and_b64 vcc, exec, s[2:3]
	v_mov_b32_e32 v11, 0
	v_mov_b32_e32 v12, 0
	v_mov_b32_e32 v13, 0
	s_cbranch_vccnz .LBB0_738
	global_load_dwordx4 v[10:13], v[42:43], off offset:3072 nt
.LBB0_738:
	s_waitcnt vmcnt(3)
	v_pk_mul_f32 v[54:55], v[80:81], v[80:81]
	v_pk_mul_f32 v[56:57], v[78:79], v[78:79]
	s_waitcnt vmcnt(0)
	v_mul_f32_e32 v0, v66, v66
	v_pk_mov_b32 v[58:59], v[56:57], v[54:55] op_sel:[1,0]
	v_mov_b32_e32 v57, v55
	v_pk_add_f32 v[54:55], v[58:59], v[56:57]
	v_pk_mul_f32 v[56:57], v[76:77], v[76:77]
	v_pk_mul_f32 v[58:59], v[74:75], v[74:75]
	v_pk_add_f32 v[54:55], v[54:55], v[54:55] op_sel:[0,1] op_sel_hi:[1,0]
	v_pk_mov_b32 v[60:61], v[58:59], v[56:57] op_sel:[1,0]
	v_mov_b32_e32 v59, v57
	v_pk_add_f32 v[56:57], v[60:61], v[58:59]
	v_mul_f32_e32 v58, v67, v67
	v_pk_add_f32 v[56:57], v[56:57], v[56:57] op_sel:[0,1] op_sel_hi:[1,0]
	v_mov_b32_e32 v55, v0
	v_mov_b32_e32 v57, v58
	v_mul_f32_e32 v0, v71, v71
	v_mul_f32_e32 v59, v68, v68
	v_pk_add_f32 v[54:55], v[54:55], v[56:57]
	v_pk_fma_f32 v[56:57], v[70:71], v[70:71], v[0:1] op_sel_hi:[1,1,0]
	v_mul_f32_e32 v0, v73, v73
	v_mul_f32_e32 v60, v69, v69
	v_mov_b32_e32 v57, v59
	v_pk_fma_f32 v[58:59], v[72:73], v[72:73], v[0:1] op_sel_hi:[1,1,0]
	global_load_dwordx4 v[42:45], v[84:85], off nt
	global_load_dwordx4 v[62:65], v[84:85], off offset:1024 nt
	v_mov_b32_e32 v59, v60
	v_pk_add_f32 v[56:57], v[56:57], v[58:59]
	global_load_dwordx4 v[58:61], v[84:85], off offset:2048 nt
	v_pk_add_f32 v[54:55], v[54:55], v[56:57]
	s_lshl_b64 s[12:13], s[14:15], 11
	v_add_f32_e32 v0, v54, v55
	ds_bpermute_b32 v54, v88, v0
	s_waitcnt lgkmcnt(0)
	v_add_f32_e32 v0, v0, v54
	ds_bpermute_b32 v54, v89, v0
	s_waitcnt lgkmcnt(0)
	v_add_f32_e32 v0, v0, v54
	ds_bpermute_b32 v54, v90, v0
	s_waitcnt lgkmcnt(0)
	v_add_f32_e32 v0, v0, v54
	ds_bpermute_b32 v54, v91, v0
	s_waitcnt lgkmcnt(0)
	v_add_f32_e32 v0, v0, v54
	ds_bpermute_b32 v54, v92, v0
	s_waitcnt lgkmcnt(0)
	v_add_f32_e32 v0, v0, v54
	ds_bpermute_b32 v54, v93, v0
	s_waitcnt lgkmcnt(0)
; DI unsigned cvtpk(float lo, float hi) { f32x2_t v = {lo, hi}; bf16x2_t b = __builtin_convertvector(v, bf16x2_t); return __builtin_bit_cast(unsigned, b); }
; template <bool BF> DI void norm_rows4(float* src, const float* gw, bf16* dstb, int r0, int stride, int lane) {
;     ...
;     for (int k = 0; k < 4; ++k) { const int r = r0 + k * stride; float s = 0.f;
; #pragma unroll
;         for (int j = 0; j < 4; ++j) s += (v[k][j].x * v[k][j].x + v[k][j].y * v[k][j].y) + (v[k][j].z * v[k][j].z + v[k][j].w * v[k][j].w);
;         const float rs = 1.f / sqrtf(wave_sum(s) * (1.f / D) + 1e-6f);
;         if (r < M) {
; #pragma unroll
;             for (int j = 0; j < 4; ++j) {
;                 const f32x4 y = (f32x4){v[k][j].x * rs * gg[j].x, v[k][j].y * rs * gg[j].y, v[k][j].z * rs * gg[j].z, v[k][j].w * rs * gg[j].w};
;                 if (BF) { u32x2 w; w.x = cvtpk(y.x, y.y); w.y = cvtpk(y.z, y.w); *(u32x2*)(dstb + (size_t)r * D + 4 * lane + 256 * j) = w; }
;                 else *(f32x4*)(src + (size_t)r * D + 4 * lane + 256 * j) = y;
;             }
;         }
;     }
	v_add_f32_e32 v0, v0, v54
	v_fmamk_f32 v0, v0, 0x3a800000, v178
	v_mul_f32_e32 v54, 0x4f800000, v0
	v_cmp_gt_f32_e32 vcc, s62, v0
	s_nop 1
	v_cndmask_b32_e32 v0, v0, v54, vcc
	global_load_dwordx4 v[54:57], v[84:85], off offset:3072 nt
	v_sqrt_f32_e32 v94, v0
	s_nop 0
	v_add_u32_e32 v95, -1, v94
	v_add_u32_e32 v96, 1, v94
	v_fma_f32 v97, -v95, v94, v0
	v_fma_f32 v98, -v96, v94, v0
	v_cmp_ge_f32_e64 s[0:1], 0, v97
	s_nop 1
	v_cndmask_b32_e64 v94, v94, v95, s[0:1]
	v_cmp_lt_f32_e64 s[0:1], 0, v98
	s_nop 1
	v_cndmask_b32_e64 v94, v94, v96, s[0:1]
	v_mul_f32_e32 v95, 0x37800000, v94
	v_cndmask_b32_e32 v94, v94, v95, vcc
	v_cmp_class_f32_e32 vcc, v0, v179
	s_nop 1
	v_cndmask_b32_e32 v0, v94, v0, vcc
	v_div_scale_f32 v96, s[0:1], v0, v0, 1.0
	v_rcp_f32_e32 v97, v96
	v_div_scale_f32 v98, vcc, 1.0, v0, 1.0
	v_lshl_add_u64 v[94:95], v[86:87], 0, s[12:13]
	v_fma_f32 v99, -v96, v97, 1.0
	v_fmac_f32_e32 v97, v99, v97
	v_mul_f32_e32 v99, v98, v97
	v_fma_f32 v100, -v96, v99, v98
	v_fmac_f32_e32 v99, v100, v97
	v_fma_f32 v96, -v96, v99, v98
	v_div_fmas_f32 v96, v96, v97, v99
	v_div_fixup_f32 v0, v96, v0, 1.0
	v_pk_mul_f32 v[78:79], v[78:79], v[0:1] op_sel_hi:[1,0]
	v_mul_f32_e32 v96, v41, v41
	s_waitcnt vmcnt(3)
	v_pk_mul_f32 v[78:79], v[42:43], v[78:79]
	v_fmac_f32_e32 v96, v40, v40
	v_cvt_pk_bf16_f32 v78, v78, v79
	v_mul_f32_e32 v79, v39, v39
	v_fmac_f32_e32 v79, v38, v38
	v_add_f32_e32 v79, v79, v96
	v_mul_f32_e32 v96, v35, v35
	v_mul_f32_e32 v97, v37, v37
	v_fmac_f32_e32 v96, v34, v34
	v_fmac_f32_e32 v97, v36, v36
	v_add_f32_e32 v96, v96, v97
	v_add_f32_e32 v79, v79, v96
	v_mul_f32_e32 v96, v51, v51
	v_mul_f32_e32 v97, v53, v53
	v_fmac_f32_e32 v96, v50, v50
	v_fmac_f32_e32 v97, v52, v52
	v_add_f32_e32 v96, v96, v97
	v_add_f32_e32 v79, v79, v96
	v_mul_f32_e32 v96, v47, v47
	v_mul_f32_e32 v97, v49, v49
	v_fmac_f32_e32 v96, v46, v46
	v_fmac_f32_e32 v97, v48, v48
	v_add_f32_e32 v96, v96, v97
	v_add_f32_e32 v96, v79, v96
	ds_bpermute_b32 v97, v88, v96
	v_pk_mul_f32 v[80:81], v[80:81], v[0:1] op_sel_hi:[1,0]
	v_pk_mul_f32 v[74:75], v[74:75], v[0:1] op_sel_hi:[1,0]
	v_pk_mul_f32 v[80:81], v[44:45], v[80:81]
	v_pk_mul_f32 v[76:77], v[76:77], v[0:1] op_sel_hi:[1,0]
	v_cvt_pk_bf16_f32 v79, v80, v81
	global_store_dwordx2 v[94:95], v[78:79], off
	s_waitcnt lgkmcnt(0)
	v_add_f32_e32 v78, v96, v97
	ds_bpermute_b32 v79, v89, v78
	s_waitcnt vmcnt(3)
	v_pk_mul_f32 v[74:75], v[62:63], v[74:75]
	v_pk_mul_f32 v[76:77], v[64:65], v[76:77]
	v_cvt_pk_bf16_f32 v74, v74, v75
	v_cvt_pk_bf16_f32 v75, v76, v77
	s_waitcnt lgkmcnt(0)
	v_add_f32_e32 v76, v78, v79
	ds_bpermute_b32 v77, v90, v76
	global_store_dwordx2 v[94:95], v[74:75], off offset:512
	v_pk_mul_f32 v[70:71], v[70:71], v[0:1] op_sel_hi:[1,0]
	v_pk_mul_f32 v[72:73], v[72:73], v[0:1] op_sel_hi:[1,0]
	s_waitcnt vmcnt(3)
	v_pk_mul_f32 v[70:71], v[58:59], v[70:71]
	s_waitcnt lgkmcnt(0)
	v_add_f32_e32 v74, v76, v77
	ds_bpermute_b32 v75, v91, v74
	v_pk_mul_f32 v[72:73], v[60:61], v[72:73]
	v_cvt_pk_bf16_f32 v70, v70, v71
	v_cvt_pk_bf16_f32 v71, v72, v73
	v_pk_mul_f32 v[66:67], v[66:67], v[0:1] op_sel_hi:[1,0]
	s_waitcnt lgkmcnt(0)
	v_add_f32_e32 v72, v74, v75
	ds_bpermute_b32 v73, v92, v72
	global_store_dwordx2 v[94:95], v[70:71], off offset:1024
	s_waitcnt vmcnt(3)
	v_pk_mul_f32 v[70:71], v[54:55], v[66:67]
	v_pk_mul_f32 v[66:67], v[68:69], v[0:1] op_sel_hi:[1,0]
	v_cvt_pk_bf16_f32 v70, v70, v71
	s_waitcnt lgkmcnt(0)
	v_add_f32_e32 v0, v72, v73
	v_pk_mul_f32 v[68:69], v[56:57], v[66:67]
	ds_bpermute_b32 v66, v93, v0
	v_cvt_pk_bf16_f32 v71, v68, v69
	s_and_b64 vcc, exec, s[6:7]
	global_store_dwordx2 v[94:95], v[70:71], off offset:1536
	s_cbranch_vccnz .LBB0_740
	s_waitcnt lgkmcnt(0)
	v_add_f32_e32 v0, v0, v66
	v_fmamk_f32 v0, v0, 0x3a800000, v178
	v_mul_f32_e32 v66, 0x4f800000, v0
	v_cmp_gt_f32_e32 vcc, s62, v0
	s_nop 1
	v_cndmask_b32_e32 v0, v0, v66, vcc
	v_sqrt_f32_e32 v66, v0
	s_nop 0
	v_add_u32_e32 v67, -1, v66
	v_fma_f32 v69, -v67, v66, v0
	v_add_u32_e32 v68, 1, v66
	v_cmp_ge_f32_e64 s[0:1], 0, v69
	s_nop 1
	v_cndmask_b32_e64 v67, v66, v67, s[0:1]
	v_fma_f32 v66, -v68, v66, v0
	v_cmp_lt_f32_e64 s[0:1], 0, v66
	s_nop 1
	v_cndmask_b32_e64 v66, v67, v68, s[0:1]
	v_mul_f32_e32 v67, 0x37800000, v66
	v_cndmask_b32_e32 v66, v66, v67, vcc
	v_cmp_class_f32_e32 vcc, v0, v179
	s_nop 1
	v_cndmask_b32_e32 v0, v66, v0, vcc
	v_div_scale_f32 v66, s[0:1], v0, v0, 1.0
	v_rcp_f32_e32 v67, v66
	s_lshl_b64 s[0:1], s[8:9], 11
	v_fma_f32 v68, -v66, v67, 1.0
	v_fmac_f32_e32 v67, v68, v67
	v_div_scale_f32 v68, vcc, 1.0, v0, 1.0
	v_mul_f32_e32 v69, v68, v67
	v_fma_f32 v70, -v66, v69, v68
	v_fmac_f32_e32 v69, v70, v67
	v_fma_f32 v66, -v66, v69, v68
	v_div_fmas_f32 v66, v66, v67, v69
	v_div_fixup_f32 v0, v66, v0, 1.0
	v_pk_mul_f32 v[34:35], v[34:35], v[0:1] op_sel_hi:[1,0]
	v_pk_mul_f32 v[36:37], v[36:37], v[0:1] op_sel_hi:[1,0]
	v_pk_mul_f32 v[34:35], v[62:63], v[34:35]
	v_pk_mul_f32 v[36:37], v[64:65], v[36:37]
	v_lshl_add_u64 v[66:67], v[86:87], 0, s[0:1]
	v_cvt_pk_bf16_f32 v34, v34, v35
	v_cvt_pk_bf16_f32 v35, v36, v37
	global_store_dwordx2 v[66:67], v[34:35], off offset:512
	v_pk_mul_f32 v[34:35], v[50:51], v[0:1] op_sel_hi:[1,0]
	v_pk_mul_f32 v[36:37], v[52:53], v[0:1] op_sel_hi:[1,0]
	v_pk_mul_f32 v[34:35], v[58:59], v[34:35]
	v_pk_mul_f32 v[36:37], v[60:61], v[36:37]
	v_cvt_pk_bf16_f32 v34, v34, v35
	v_cvt_pk_bf16_f32 v35, v36, v37
	v_pk_mul_f32 v[38:39], v[38:39], v[0:1] op_sel_hi:[1,0]
	v_pk_mul_f32 v[40:41], v[40:41], v[0:1] op_sel_hi:[1,0]
	global_store_dwordx2 v[66:67], v[34:35], off offset:1024
	v_pk_mul_f32 v[34:35], v[46:47], v[0:1] op_sel_hi:[1,0]
	v_pk_mul_f32 v[36:37], v[48:49], v[0:1] op_sel_hi:[1,0]
	v_pk_mul_f32 v[38:39], v[42:43], v[38:39]
	v_pk_mul_f32 v[40:41], v[44:45], v[40:41]
	v_pk_mul_f32 v[34:35], v[54:55], v[34:35]
	v_pk_mul_f32 v[36:37], v[56:57], v[36:37]
	v_cvt_pk_bf16_f32 v38, v38, v39
	v_cvt_pk_bf16_f32 v39, v40, v41
	v_cvt_pk_bf16_f32 v34, v34, v35
	v_cvt_pk_bf16_f32 v35, v36, v37
	global_store_dwordx2 v[66:67], v[38:39], off
	global_store_dwordx2 v[66:67], v[34:35], off offset:1536
